# panel-ordered GEMMs: the half-filled last round (128 tiles) is spread over 16 workgroups on each of the 8 XCDs instead of all workgroups of XCDs 0-3
# baseline (speedup 1.0000x reference)
; template <bool OVL, bool PANEL = false, class Epi>
; __device__ __forceinline__ void gemm_phase(const bf16_t* __restrict__ A, long lda, const bf16_t* __restrict__ Bt, long ldb, int nM, int nN, int K,
;                                            const Epi& epi, bf16_t* shm, int w0) {
;     ...
;     have = PANEL ? tile_next_panel((long)(it + 1) * gridDim.x + blockIdx.x, nM, pm, pn) : tile_next((long)(it + 1) * gridDim.x + blockIdx.x, nM, nN, pm, pn);
;     if (OVL && have) { const int nbrow = pm * BM, nbcol = pn * BM;
;       STAGE(SB(0, 0), Bt, ldb, boff, nbcol, 0); STAGE(SA(0, 0), A, lda, aoff, nbrow, 0);
;       STAGE(SB(0, 1), Bt, ldb, boff, nbcol + HALF, 0); STAGE(SA(0, 1), A, lda, aoff, nbrow + HALF, 0); }
.LBB0_128:
	s_or_b64 exec, exec, s[0:1]
	s_add_i32 s24, s24, 1
	s_mul_i32 s0, s24, s62
	v_readlane_b32 s4, v252, 45
	s_mul_hi_u32 s1, s24, s62
	s_add_u32 s0, s0, s4
	v_readlane_b32 s5, v252, 46
	s_addc_u32 s1, s1, 0
	s_lshr_b64 s[4:5], s[0:1], 2
	s_lshl_b32 s2, s0, 3
	s_and_b32 s1, s4, 0xffffffc0
	s_and_b32 s2, s2, 56
	s_or_b32 s1, s1, s2
	s_bfe_u32 s2, s0, 0x30005
	s_or_b32 s2, s1, s2
	s_lshr_b32 s98, s0, 8
	s_cmp_eq_u32 s98, 4
	s_cbranch_scc0 .Llr1
	s_cmpk_eq_i32 s20, 0x120
	s_cbranch_scc0 .Llr1
	s_and_b32 s98, s0, 7
	s_lshl_b32 s98, s98, 2
	s_bfe_u32 s99, s0, 0x20005
	s_or_b32 s98, s98, s99
	s_add_i32 s2, s98, 0x100
	s_bitcmp1_b32 s0, 7
	s_cselect_b32 s2, s20, s2
.Llr1:
	s_bfe_u32 s17, s0, 0x20003
	s_cmp_ge_i32 s2, s20
	s_cselect_b64 s[4:5], -1, 0
	s_and_b64 vcc, exec, s[4:5]
	s_cbranch_vccnz .LBB0_130
	v_readlane_b32 s40, v251, 49
	s_mul_i32 s0, s17, 0x160000
	v_readlane_b32 s42, v251, 51
	v_readlane_b32 s41, v251, 50
	v_readlane_b32 s43, v251, 52
	v_readlane_b32 s44, v251, 53
	v_readlane_b32 s45, v251, 54
	v_readlane_b32 s46, v251, 55
	v_readlane_b32 s47, v251, 56
	s_add_u32 s0, s42, s0
	v_readfirstlane_b32 s6, v204
	s_addc_u32 s1, s43, 0
	v_mov_b32_e32 v0, v203
	s_mov_b32 m0, s6
	v_readfirstlane_b32 s6, v205
	v_readlane_b32 s40, v252, 20
	s_mov_b64 s[14:15], 0x58000
	v_lshl_add_u64 v[130:131], s[0:1], 0, v[0:1]
	global_load_lds_dwordx4 v0, s[0:1]
	s_mov_b32 m0, s6
	s_lshl_b32 s8, s2, 8
	s_mul_i32 s6, s2, 0x160000
	v_readlane_b32 s54, v252, 34
	v_lshl_add_u64 v[130:131], v[130:131], 0, s[14:15]
	s_mul_hi_i32 s7, s8, 0x1600
	v_readlane_b32 s55, v252, 35
	s_add_u32 s6, s54, s6
	v_readfirstlane_b32 s9, v206
	global_load_lds_dwordx4 v[130:131], off
	s_addc_u32 s7, s55, s7
	v_mov_b32_e32 v0, v203
	s_mov_b32 m0, s9
	s_mov_b64 s[26:27], 0x58000
	v_lshl_add_u64 v[130:131], s[6:7], 0, v[0:1]
	global_load_lds_dwordx4 v0, s[6:7]
	v_readfirstlane_b32 s6, v207
	v_lshl_add_u64 v[130:131], v[130:131], 0, s[14:15]
	s_mov_b32 m0, s6
	v_mov_b32_e32 v0, v203
	global_load_lds_dwordx4 v[130:131], off
	v_readfirstlane_b32 s6, v210
	v_lshl_add_u64 v[130:131], s[0:1], 0, v[0:1]
	s_mov_b64 s[0:1], 0xb0000
	v_lshl_add_u64 v[132:133], v[130:131], 0, s[0:1]
	v_readfirstlane_b32 s0, v208
	s_mov_b32 m0, s0
	s_mov_b64 s[0:1], 0x108000
	v_lshl_add_u64 v[130:131], v[130:131], 0, s[0:1]
	v_readfirstlane_b32 s0, v209
	global_load_lds_dwordx4 v[132:133], off
	s_mov_b32 m0, s0
	s_or_b32 s0, s8, 0x80
	s_mul_hi_i32 s1, s0, 0x1600
	s_mulk_i32 s0, 0x1600
	s_add_u32 s0, s54, s0
	global_load_lds_dwordx4 v[130:131], off
	s_addc_u32 s1, s55, s1
	v_mov_b32_e32 v0, v203
	s_mov_b32 m0, s6
	v_readlane_b32 s41, v252, 21
	v_lshl_add_u64 v[130:131], s[0:1], 0, v[0:1]
	global_load_lds_dwordx4 v0, s[0:1]
	v_readfirstlane_b32 s0, v211
	v_lshl_add_u64 v[130:131], v[130:131], 0, s[14:15]
	s_mov_b32 m0, s0
	v_readlane_b32 s42, v252, 22
	global_load_lds_dwordx4 v[130:131], off
	v_readlane_b32 s43, v252, 23
	v_readlane_b32 s44, v252, 24
	v_readlane_b32 s45, v252, 25
	v_readlane_b32 s46, v252, 26
	v_readlane_b32 s47, v252, 27
	v_readlane_b32 s48, v252, 28
	v_readlane_b32 s49, v252, 29
	v_readlane_b32 s50, v252, 30
	v_readlane_b32 s51, v252, 31
	v_readlane_b32 s52, v252, 32
	v_readlane_b32 s53, v252, 33

; template <bool OVL, bool PANEL = false, class Epi>
; __device__ __forceinline__ void gemm_phase(const bf16_t* __restrict__ A, long lda, const bf16_t* __restrict__ Bt, long ldb, int nM, int nN, int K,
;                                            const Epi& epi, bf16_t* shm, int w0) {
;     ...
;     have = PANEL ? tile_next_panel((long)(it + 1) * gridDim.x + blockIdx.x, nM, pm, pn) : tile_next((long)(it + 1) * gridDim.x + blockIdx.x, nM, nN, pm, pn);
;     if (OVL && have) { const int nbrow = pm * BM, nbcol = pn * BM;
;       STAGE(SB(0, 0), Bt, ldb, boff, nbcol, 0); STAGE(SA(0, 0), A, lda, aoff, nbrow, 0);
;       STAGE(SB(0, 1), Bt, ldb, boff, nbcol + HALF, 0); STAGE(SA(0, 1), A, lda, aoff, nbrow + HALF, 0); }
.LBB0_475:
	s_or_b64 exec, exec, s[0:1]
	s_add_i32 s31, s31, 1
	s_mul_i32 s0, s31, s62
	v_readlane_b32 s6, v252, 45
	s_mul_hi_u32 s1, s31, s62
	s_add_u32 s0, s0, s6
	v_readlane_b32 s7, v252, 46
	s_addc_u32 s1, s1, 0
	s_lshr_b64 s[6:7], s[0:1], 2
	s_lshl_b32 s2, s0, 3
	s_and_b32 s1, s6, 0xffffffc0
	s_and_b32 s2, s2, 56
	s_or_b32 s1, s1, s2
	s_bfe_u32 s2, s0, 0x30005
	s_or_b32 s2, s1, s2
	s_lshr_b32 s98, s0, 8
	s_cmp_eq_u32 s98, 4
	s_cbranch_scc0 .Llr0
	s_cmpk_eq_i32 s17, 0x120
	s_cbranch_scc0 .Llr0
	s_and_b32 s98, s0, 7
	s_lshl_b32 s98, s98, 2
	s_bfe_u32 s99, s0, 0x20005
	s_or_b32 s98, s98, s99
	s_add_i32 s2, s98, 0x100
	s_bitcmp1_b32 s0, 7
	s_cselect_b32 s2, s17, s2
.Llr0:
	s_bfe_u32 s18, s0, 0x20003
	s_cmp_ge_i32 s2, s17
	s_cselect_b64 s[80:81], -1, 0
	s_and_b64 vcc, exec, s[80:81]
	s_cbranch_vccnz .LBB0_477
	v_readlane_b32 s44, v252, 3
	s_lshl_b32 s0, s18, 19
	v_readlane_b32 s58, v252, 17
	v_readlane_b32 s59, v252, 18
	s_add_u32 s0, s58, s0
	v_readlane_b32 s45, v252, 4
	v_readlane_b32 s46, v252, 5
	v_readlane_b32 s47, v252, 6
	v_readlane_b32 s48, v252, 7
	v_readlane_b32 s49, v252, 8
	v_readlane_b32 s50, v252, 9
	v_readlane_b32 s51, v252, 10
	v_readlane_b32 s52, v252, 11
	v_readlane_b32 s53, v252, 12
	v_readlane_b32 s54, v252, 13
	v_readlane_b32 s55, v252, 14
	v_readlane_b32 s56, v252, 15
	v_readlane_b32 s57, v252, 16
	s_addc_u32 s1, s59, 0
	s_lshl_b32 s6, s2, 8
	s_ashr_i32 s7, s6, 31
	v_readlane_b32 s44, v252, 20
	v_mov_b32_e32 v0, v221
	v_readfirstlane_b32 s5, v222
	s_lshl_b64 s[8:9], s[6:7], 11
	v_readlane_b32 s50, v252, 26
	s_mov_b32 m0, s5
	v_lshl_add_u64 v[130:131], s[0:1], 0, v[0:1]
	s_mov_b64 s[12:13], 0x20000
	v_readfirstlane_b32 s5, v223
	v_readlane_b32 s51, v252, 27
	s_add_u32 s8, s50, s8
	global_load_lds_dwordx4 v0, s[0:1]
	v_lshl_add_u64 v[130:131], v[130:131], 0, s[12:13]
	s_mov_b32 m0, s5
	s_addc_u32 s9, s51, s9
	v_mov_b32_e32 v0, v221
	v_readfirstlane_b32 s5, v234
	global_load_lds_dwordx4 v[130:131], off
	s_mov_b32 m0, s5
	v_lshl_add_u64 v[130:131], s[8:9], 0, v[0:1]
	v_readfirstlane_b32 s5, v235
	global_load_lds_dwordx4 v0, s[8:9]
	v_lshl_add_u64 v[130:131], v[130:131], 0, s[12:13]
	s_mov_b32 m0, s5
	v_mov_b32_e32 v0, v221
	global_load_lds_dwordx4 v[130:131], off
	v_readfirstlane_b32 s5, v238
	v_lshl_add_u64 v[130:131], s[0:1], 0, v[0:1]
	s_mov_b64 s[0:1], 0x40000
	v_lshl_add_u64 v[132:133], v[130:131], 0, s[0:1]
	v_readfirstlane_b32 s0, v236
	s_mov_b32 m0, s0
	s_mov_b64 s[0:1], 0x60000
	v_lshl_add_u64 v[130:131], v[130:131], 0, s[0:1]
	v_readfirstlane_b32 s0, v237
	global_load_lds_dwordx4 v[132:133], off
	s_mov_b32 m0, s0
	s_or_b32 s0, s6, 0x80
	s_ashr_i32 s1, s0, 31
	s_lshl_b64 s[0:1], s[0:1], 11
	s_add_u32 s0, s50, s0
	global_load_lds_dwordx4 v[130:131], off
	s_addc_u32 s1, s51, s1
	v_mov_b32_e32 v0, v221
	s_mov_b32 m0, s5
	v_readlane_b32 s45, v252, 21
	v_lshl_add_u64 v[130:131], s[0:1], 0, v[0:1]
	global_load_lds_dwordx4 v0, s[0:1]
	v_readfirstlane_b32 s0, v239
	v_lshl_add_u64 v[130:131], v[130:131], 0, s[12:13]
	s_mov_b32 m0, s0
	v_readlane_b32 s46, v252, 22
	global_load_lds_dwordx4 v[130:131], off
	v_readlane_b32 s47, v252, 23
	v_readlane_b32 s48, v252, 24
	v_readlane_b32 s49, v252, 25
	v_readlane_b32 s52, v252, 28
	v_readlane_b32 s53, v252, 29
	v_readlane_b32 s54, v252, 30
	v_readlane_b32 s55, v252, 31
	v_readlane_b32 s56, v252, 32
	v_readlane_b32 s57, v252, 33
	v_readlane_b32 s58, v252, 34
	v_readlane_b32 s59, v252, 35
